# lean13 = lean12 + rsqrt denormal fixup removed at 3 more sites (keeping the unscaled result register written)
# baseline (speedup 1.0000x reference)
;     __device__ __forceinline__ void operator()(const f32x4 (&acc)[2][2][4][2], const Unit& u, int wr, int wc, int, int) const {
;     ...
;             for (int mm = 0; mm < 2; ++mm) { const int m = (ab & 1) * 2 + mm;
;                 const int row = row0 + ai * HALF + m * 16; const float rs = rstd_from_quarter(pq[mm], fq * 16 + fr);
;                 float v0[8], v1[8];
; #pragma unroll
;                 for (int n = 0; n < 2; ++n)
; #pragma unroll
;                     for (int i = 0; i < 4; ++i) { v0[n * 4 + i] = acc[ai][0][m][n][i] * rs; v1[n * 4 + i] = acc[ai][1][m][n][i] * rs; }
;                 bf16_t* zr = Z + (size_t)row * ZP + (tile < 5 ? tile : 0) * 256;
;                 const int bl_ = row >> 12, sq_ = row & (SEQ - 1);
;                 if (tile >= 5 && tile <= 8) {
;                     const v4f c0 = cs[mm][0], c1 = cs[mm][1], s0 = cs[mm][2], s1 = cs[mm][3];
;                     const float cc[8] = {c0.x, c0.y, c0.z, c0.w, c1.x, c1.y, c1.z, c1.w}, sn[8] = {s0.x, s0.y, s0.z, s0.w, s1.x, s1.y, s1.z, s1.w};
;                     const float qs = tile < 7 ? QC2 : 1.0f;
;                     float o0[8], o1[8];
; #pragma unroll
;                     for (int i = 0; i < 8; ++i) { o0[i] = (v0[i] * cc[i] - v1[i] * sn[i]) * qs; o1[i] = (v1[i] * cc[i] + v0[i] * sn[i]) * qs; }
;                     bf16_t* dst = (tile < 7 ? QC : KC) + ((size_t)((bl_ * 8 + ((tile - 5) & 1) * 4 + wc) * SEQ + sq_)) * 64 + 8 * fq;
;                     *(u32x4*)(dst) = pack8(o0);
;                     *(u32x4*)(dst + 32) = pack8(o1);
;                 } else if (tile == 23) {
;                     if (wc == 0 && fq == 0) {
;                         float* mo = mif + (size_t)row * 8;
;                         *(v4f*)(mo) = (v4f){v0[0] + gate_b[0], v0[1] + gate_b[1], v0[2] + gate_b[2], v0[3] + gate_b[3]};
;                         *(v4f*)(mo + 4) = (v4f){v0[4] + gate_b[4], v0[5] + gate_b[5], v0[6] + gate_b[6], v0[7] + gate_b[7]};
;                     }
;                 } else if (tile == 9 || tile == 10) {
;                     bf16_t* d0 = VC + ((size_t)(((bl_ * 4 + (tile - 9) * 2 + 0) * 2 + (wc >> 1)) * SEQ + sq_)) * 64 + (wc & 1) * 32 + 8 * fq;
;                     bf16_t* d1 = VC + ((size_t)(((bl_ * 4 + (tile - 9) * 2 + 1) * 2 + (wc >> 1)) * SEQ + sq_)) * 64 + (wc & 1) * 32 + 8 * fq;
;                     *(u32x4*)d0 = pack8(v0); *(u32x4*)d1 = pack8(v1);
.LBB0_1155:
	s_nop 1
	v_mov_b32_e32 v148, v161
	v_mov_b32_e32 v149, v162
	v_mov_b32_e32 v161, v163
	v_pk_add_f32 v[148:149], v[148:149], v[160:161]
	s_mov_b64 s[22:23], -1
	v_add_f32_e32 v145, v148, v149
	ds_bpermute_b32 v147, v194, v145
	s_waitcnt lgkmcnt(0)
	v_add_f32_e32 v145, v145, v147
	ds_bpermute_b32 v147, v195, v145
	s_waitcnt lgkmcnt(0)
	v_add_f32_e32 v145, v145, v147
	v_fmamk_f32 v145, v145, 0x3a800000, v235
	s_nop 1
	v_rsq_f32_e32 v145, v145
	v_and_b32_e32 v147, 0xfdf, v188
	s_nop 0
	v_mov_b32_e32 v152, v145
	v_pk_mul_f32 v[150:151], v[132:133], v[152:153] op_sel_hi:[1,0]
	v_pk_mul_f32 v[132:133], v[136:137], v[152:153] op_sel_hi:[1,0]
	v_cndmask_b32_e64 v136, 0, 1, s[94:95]
	v_cmp_ne_u32_e64 s[10:11], 1, v136
	v_cndmask_b32_e64 v136, 0, 1, s[96:97]
	v_pk_mul_f32 v[148:149], v[140:141], v[152:153] op_sel_hi:[1,0]
	v_pk_mul_f32 v[140:141], v[142:143], v[152:153] op_sel_hi:[1,0]
	v_pk_mul_f32 v[142:143], v[134:135], v[152:153] op_sel_hi:[1,0]
	v_pk_mul_f32 v[134:135], v[128:129], v[152:153] op_sel_hi:[1,0]
	v_pk_mul_f32 v[128:129], v[138:139], v[152:153] op_sel_hi:[1,0]
	v_pk_mul_f32 v[130:131], v[130:131], v[152:153] op_sel_hi:[1,0]
	s_andn2_b64 vcc, exec, s[94:95]
	v_cmp_ne_u32_e64 s[8:9], 1, v136
	s_movk_i32 s96, 0x4000
	s_cbranch_vccnz .LBB0_1171
	s_and_b64 vcc, exec, s[8:9]
	s_cbranch_vccnz .LBB0_1166
	s_andn2_b64 vcc, exec, s[92:93]
	s_cbranch_vccnz .LBB0_1163
	v_mov_b64_e32 v[136:137], s[12:13]
	v_mad_i64_i32 v[136:137], s[22:23], v188, s29, v[136:137]
	s_andn2_b64 vcc, exec, s[90:91]
	s_mov_b64 s[22:23], -1
	s_cbranch_vccnz .LBB0_1160
	v_lshl_add_u64 v[138:139], s[88:89], 1, v[136:137]
	s_lshl_b32 s30, s68, 1
	v_lshl_add_u64 v[138:139], v[138:139], 0, s[30:31]
	v_mov_b32_e32 v145, v221
	v_cvt_pk_bf16_f32 v152, v148, v149
	v_cvt_pk_bf16_f32 v153, v140, v141
	v_cvt_pk_bf16_f32 v154, v132, v133
	v_cvt_pk_bf16_f32 v155, v128, v129
	v_lshl_add_u64 v[138:139], v[138:139], 0, v[144:145]
	global_store_dwordx4 v[138:139], v[152:155], off
	s_mov_b64 s[22:23], 0
	s_nop 0
	v_cvt_pk_bf16_f32 v152, v150, v151
	v_cvt_pk_bf16_f32 v153, v142, v143
	v_cvt_pk_bf16_f32 v154, v134, v135
	v_cvt_pk_bf16_f32 v155, v130, v131
	global_store_dwordx4 v[138:139], v[152:155], off offset:256

; __device__ __forceinline__ v4u pack8(const float* x) { v4u o; o.x = pk2(x[0], x[1]); o.y = pk2(x[2], x[3]); o.z = pk2(x[4], x[5]); o.w = pk2(x[6], x[7]); return o; }
; __device__ __forceinline__ size_t tl(int row, int col, int K) { return (size_t)(row >> 8) * ((size_t)256 * K) + (size_t)(col >> 6) * (256 * 64) + (size_t)((row & 255) * 64 + (col & 63)); }
; __device__ __forceinline__ float rstd_from_quarter(const v4f a, int ln) {
;     float s = (a.x + a.y) + (a.z + a.w);
;     s += __int_as_float(__builtin_amdgcn_ds_bpermute((ln ^ 16) << 2, __float_as_int(s))); s += __int_as_float(__builtin_amdgcn_ds_bpermute((ln ^ 32) << 2, __float_as_int(s)));
;     return rsqrtf(s * (1.0f / DM) + EPS);
; }
;     __device__ __forceinline__ void operator()(const f32x4 (&acc)[2][2][4][2], const Unit& u, int wr, int wc, int, int) const {
;         int t_ = threadIdx.x; asm volatile("" : "+v"(t_)); const int fr = t_ & 15, fq = (t_ >> 4) & 3;
;         const int row0 = u.pm * BM + wr * 64 + fr, col0 = u.pn * HALF + wc * 32 + 8 * fq;
;         v4f pq[2][4];
; #pragma unroll
;         for (int ai = 0; ai < 2; ++ai)
; #pragma unroll
;             for (int m = 0; m < 4; ++m) pq[ai][m] = *(const v4f*)(ssp + (size_t)(row0 + ai * HALF + m * 16) * 16 + 4 * fq);
;         asm volatile("" ::: "memory");
; #pragma unroll
;         for (int ai = 0; ai < 2; ++ai)
; #pragma unroll
;             for (int m = 0; m < 4; ++m) {
;                 const int row = row0 + ai * HALF + m * 16; const float rs = rstd_from_quarter(pq[ai][m], fq * 16 + fr);
;                 float h[8];
; #pragma unroll
;                 for (int n = 0; n < 2; ++n) { const f32x4 g = acc[ai][0][m][n] * rs, uu = acc[ai][1][m][n] * rs; const f32x4 hv = (g * sigmoid4(g)) * uu;
;                     h[n * 4 + 0] = hv[0]; h[n * 4 + 1] = hv[1]; h[n * 4 + 2] = hv[2]; h[n * 4 + 3] = hv[3]; }
;                 __builtin_nontemporal_store(pack8(h), (u32x4*)(O + tl(row, col0, FF)));
.LBB0_1359:
	s_lshl_b32 s91, s10, 8
	s_add_i32 s91, s91, s77
	v_and_or_b32 v232, v230, 15, s91
	v_bfe_u32 v233, v230, 4, 2
	v_lshlrev_b32_e32 v232, 6, v232
	v_lshl_add_u32 v232, v233, 4, v232
	v_add_u32_e32 v233, 0x2000, v232
	s_lshl_b32 s9, s16, 8
	v_mov_b32_e32 v142, v230
	s_add_i32 s9, s9, s52
	s_mov_b32 s16, 0x358637bd
	v_and_or_b32 v136, v142, 15, s9
	v_bfe_u32 v143, v142, 4, 2
	v_or_b32_e32 v132, 16, v136
	v_lshlrev_b32_e32 v220, 4, v143
	v_ashrrev_i32_e32 v137, 31, v136
	v_ashrrev_i32_e32 v133, 31, v132
	v_lshl_add_u64 v[138:139], s[4:5], 0, v[220:221]
	v_lshlrev_b64 v[128:129], 6, v[136:137]
	v_lshlrev_b64 v[132:133], 6, v[132:133]
	v_lshl_add_u64 v[140:141], v[138:139], 0, v[128:129]
	v_lshl_add_u64 v[132:133], v[138:139], 0, v[132:133]
	v_mov_b64_e32 v[128:129], v[208:209]
	v_mov_b64_e32 v[130:131], v[210:211]
	global_load_dwordx4 v[208:211], v232, s[92:93]
	v_lshlrev_b32_e32 v137, 2, v142
	v_mov_b64_e32 v[132:133], v[212:213]
	v_mov_b64_e32 v[134:135], v[214:215]
	global_load_dwordx4 v[212:215], v232, s[92:93] offset:1024
	v_or_b32_e32 v142, 32, v136
	v_or_b32_e32 v160, 48, v136
	v_add_u32_e32 v158, 0x80, v136
	v_lshl_or_b32 v166, v143, 3, s56
	v_lshlrev_b32_e32 v136, 6, v136
	v_ashrrev_i32_e32 v143, 31, v142
	v_bitop3_b32 v165, v137, 64, v244 bitop3:0x6c
	v_bitop3_b32 v164, v137, s90, v244 bitop3:0x6c
	v_ashrrev_i32_e32 v161, 31, v160
	v_and_or_b32 v167, v136, s84, v166
	v_lshlrev_b64 v[136:137], 6, v[142:143]
	v_lshlrev_b64 v[142:143], 6, v[160:161]
	v_lshl_add_u64 v[136:137], v[138:139], 0, v[136:137]
	v_lshl_add_u64 v[142:143], v[138:139], 0, v[142:143]
	v_mov_b64_e32 v[168:169], v[216:217]
	v_mov_b64_e32 v[170:171], v[218:219]
	global_load_dwordx4 v[216:219], v232, s[92:93] offset:2048
	v_mov_b64_e32 v[172:173], v[222:223]
	v_mov_b64_e32 v[174:175], v[224:225]
	global_load_dwordx4 v[222:225], v232, s[92:93] offset:3072
	v_ashrrev_i32_e32 v159, 31, v158
	v_lshlrev_b64 v[160:161], 6, v[158:159]
	v_lshl_add_u64 v[138:139], v[138:139], 0, v[160:161]
	s_lshl_b32 s11, s17, 7
	v_mov_b64_e32 v[156:157], s[16:17]
	s_or_b32 s11, s11, s53
	s_ashr_i32 s16, s11, 6
	s_ashr_i32 s17, s16, 31
	s_ashr_i32 s9, s9, 8
	s_lshl_b64 s[16:17], s[16:17], 15
	s_add_u32 s16, s50, s16
	v_lshlrev_b32_e32 v220, 1, v167
	s_addc_u32 s17, s51, s17
	v_lshl_add_u64 v[176:177], s[16:17], 0, v[220:221]
	v_mov_b32_e32 v160, v129
	v_mov_b32_e32 v161, v130
	v_mov_b32_e32 v129, v131
	v_mov_b32_e32 v130, v133
	v_mov_b32_e32 v131, v134
	v_mov_b32_e32 v133, v135
	v_pk_add_f32 v[128:129], v[160:161], v[128:129]
	v_pk_add_f32 v[130:131], v[130:131], v[132:133]
	v_mov_b32_e32 v133, v128
	v_mov_b32_e32 v132, v130
	v_mov_b32_e32 v128, v131
	v_pk_add_f32 v[128:129], v[132:133], v[128:129]
	ds_bpermute_b32 v131, v165, v129
	ds_bpermute_b32 v130, v165, v128
	v_add_co_u32_e32 v160, vcc, s80, v140
	s_waitcnt lgkmcnt(0)
	v_pk_add_f32 v[178:179], v[128:129], v[130:131]
	ds_bpermute_b32 v181, v164, v179
	ds_bpermute_b32 v180, v164, v178
	v_addc_co_u32_e32 v161, vcc, 0, v141, vcc
	v_mov_b64_e32 v[140:141], v[226:227]
	v_mov_b64_e32 v[142:143], v[228:229]
	global_load_dwordx4 v[226:229], v233, s[92:93]
	s_nop 0
	v_mov_b64_e32 v[136:137], v[240:241]
	v_mov_b64_e32 v[138:139], v[242:243]
	global_load_dwordx4 v[240:243], v233, s[92:93] offset:1024
	v_mov_b64_e32 v[132:133], v[246:247]
	v_mov_b64_e32 v[134:135], v[248:249]
	global_load_dwordx4 v[246:249], v233, s[92:93] offset:2048
	v_mov_b64_e32 v[128:129], v[250:251]
	v_mov_b64_e32 v[130:131], v[252:253]
	global_load_dwordx4 v[250:253], v233, s[92:93] offset:3072
	s_waitcnt lgkmcnt(0)
	v_pk_add_f32 v[160:161], v[178:179], v[180:181]
	s_nop 0
	v_pk_fma_f32 v[178:179], v[160:161], s[74:75], v[156:157] op_sel_hi:[1,0,0]
	v_mad_i64_i32 v[160:161], s[18:19], s9, v245, v[176:177]
	v_mul_f32_e32 v167, 0x4b800000, v178
	s_nop 0
	v_rsq_f32_e32 v159, v179
	s_nop 0
	s_nop 0
	v_mov_b32_e32 v176, v159
	v_pk_mul_f32 v[120:121], v[120:121], v[176:177] op_sel_hi:[1,0]
	v_pk_mul_f32 v[122:123], v[122:123], v[176:177] op_sel_hi:[1,0]
	v_pk_mul_f32 v[184:185], v[120:121], s[38:39] op_sel_hi:[1,0]
	v_pk_mul_f32 v[182:183], v[122:123], s[38:39] op_sel_hi:[1,0]
	v_exp_f32_e32 v184, v184
	v_exp_f32_e32 v182, v182
	v_exp_f32_e32 v183, v183
	v_exp_f32_e32 v185, v185
	v_pk_mul_f32 v[124:125], v[124:125], v[176:177] op_sel_hi:[1,0]
	v_pk_mul_f32 v[126:127], v[126:127], v[176:177] op_sel_hi:[1,0]
	v_pk_mul_f32 v[180:181], v[124:125], s[38:39] op_sel_hi:[1,0]
	v_pk_add_f32 v[182:183], v[182:183], 1.0 op_sel_hi:[1,0]
	v_pk_add_f32 v[184:185], v[184:185], 1.0 op_sel_hi:[1,0]
	v_exp_f32_e32 v180, v180
	v_exp_f32_e32 v181, v181
	v_rcp_f32_e32 v184, v184
	v_rcp_f32_e32 v185, v185
	v_rcp_f32_e32 v182, v182
	v_rcp_f32_e32 v183, v183
	v_pk_mul_f32 v[116:117], v[116:117], v[176:177] op_sel_hi:[1,0]
	v_pk_mul_f32 v[118:119], v[118:119], v[176:177] op_sel_hi:[1,0]
	v_pk_mul_f32 v[112:113], v[112:113], v[176:177] op_sel_hi:[1,0]
	v_pk_mul_f32 v[114:115], v[114:115], v[176:177] op_sel_hi:[1,0]
	v_pk_mul_f32 v[176:177], v[126:127], s[38:39] op_sel_hi:[1,0]
	v_pk_add_f32 v[180:181], v[180:181], 1.0 op_sel_hi:[1,0]
	v_exp_f32_e32 v176, v176
	v_exp_f32_e32 v177, v177
	v_pk_mul_f32 v[120:121], v[120:121], v[184:185]
	v_pk_mul_f32 v[122:123], v[122:123], v[182:183]
	v_cmp_gt_f32_e32 vcc, s25, v178
	v_rcp_f32_e32 v180, v180
	v_rcp_f32_e32 v181, v181
	v_pk_mul_f32 v[122:123], v[114:115], v[122:123]
	v_pk_mul_f32 v[114:115], v[112:113], v[120:121]
	v_cndmask_b32_e32 v112, v178, v167, vcc
	v_pk_add_f32 v[176:177], v[176:177], 1.0 op_sel_hi:[1,0]
	v_rsq_f32_e32 v120, v112
	v_rcp_f32_e32 v176, v176
	v_rcp_f32_e32 v177, v177
	v_pk_mul_f32 v[124:125], v[124:125], v[180:181]
; __device__ __forceinline__ v4u pack8(const float* x) { v4u o; o.x = pk2(x[0], x[1]); o.y = pk2(x[2], x[3]); o.z = pk2(x[4], x[5]); o.w = pk2(x[6], x[7]); return o; }
; __device__ __forceinline__ size_t tl(int row, int col, int K) { return (size_t)(row >> 8) * ((size_t)256 * K) + (size_t)(col >> 6) * (256 * 64) + (size_t)((row & 255) * 64 + (col & 63)); }
; __device__ __forceinline__ float rstd_from_quarter(const v4f a, int ln) {
;     float s = (a.x + a.y) + (a.z + a.w);
;     s += __int_as_float(__builtin_amdgcn_ds_bpermute((ln ^ 16) << 2, __float_as_int(s))); s += __int_as_float(__builtin_amdgcn_ds_bpermute((ln ^ 32) << 2, __float_as_int(s)));
;     return rsqrtf(s * (1.0f / DM) + EPS);
; }
;     __device__ __forceinline__ void operator()(const f32x4 (&acc)[2][2][4][2], const Unit& u, int wr, int wc, int, int) const {
;     ...
;         for (int ai = 0; ai < 2; ++ai)
; #pragma unroll
;             for (int m = 0; m < 4; ++m) {
;                 const int row = row0 + ai * HALF + m * 16; const float rs = rstd_from_quarter(pq[ai][m], fq * 16 + fr);
;                 float h[8];
; #pragma unroll
;                 for (int n = 0; n < 2; ++n) { const f32x4 g = acc[ai][0][m][n] * rs, uu = acc[ai][1][m][n] * rs; const f32x4 hv = (g * sigmoid4(g)) * uu;
;                     h[n * 4 + 0] = hv[0]; h[n * 4 + 1] = hv[1]; h[n * 4 + 2] = hv[2]; h[n * 4 + 3] = hv[3]; }
;                 __builtin_nontemporal_store(pack8(h), (u32x4*)(O + tl(row, col0, FF)));
	v_cvt_pk_bf16_f32 v114, v114, v115
	v_pk_mul_f32 v[116:117], v[116:117], v[124:125]
	v_mul_f32_e32 v115, 0x45800000, v120
	v_pk_mul_f32 v[126:127], v[126:127], v[176:177]
	v_cvt_pk_bf16_f32 v112, v116, v117
	v_cndmask_b32_e32 v116, v120, v115, vcc
	v_pk_mul_f32 v[118:119], v[118:119], v[126:127]
	v_pk_mul_f32 v[108:109], v[108:109], v[116:117] op_sel_hi:[1,0]
	v_pk_mul_f32 v[110:111], v[110:111], v[116:117] op_sel_hi:[1,0]
	v_cvt_pk_bf16_f32 v113, v118, v119
	v_pk_mul_f32 v[118:119], v[110:111], s[38:39] op_sel_hi:[1,0]
	v_pk_mul_f32 v[120:121], v[108:109], s[38:39] op_sel_hi:[1,0]
	v_exp_f32_e32 v118, v118
	v_exp_f32_e32 v120, v120
	v_exp_f32_e32 v119, v119
	v_exp_f32_e32 v121, v121
	v_cvt_pk_bf16_f32 v115, v122, v123
	global_store_dwordx4 v[160:161], v[112:115], off nt
	v_pk_mul_f32 v[100:101], v[100:101], v[116:117] op_sel_hi:[1,0]
	v_pk_mul_f32 v[102:103], v[102:103], v[116:117] op_sel_hi:[1,0]
	v_pk_add_f32 v[112:113], v[118:119], 1.0 op_sel_hi:[1,0]
	v_pk_add_f32 v[114:115], v[120:121], 1.0 op_sel_hi:[1,0]
	v_rcp_f32_e32 v112, v112
	v_rcp_f32_e32 v114, v114
	v_rcp_f32_e32 v115, v115
	v_rcp_f32_e32 v113, v113
	v_pk_mul_f32 v[104:105], v[104:105], v[116:117] op_sel_hi:[1,0]
	v_pk_mul_f32 v[106:107], v[106:107], v[116:117] op_sel_hi:[1,0]
	v_pk_mul_f32 v[108:109], v[108:109], v[114:115]
	v_pk_mul_f32 v[110:111], v[110:111], v[112:113]
	v_mov_b32_e32 v112, v169
	v_mov_b32_e32 v113, v170
	v_mov_b32_e32 v169, v171
	v_mov_b32_e32 v114, v173
	v_mov_b32_e32 v115, v174
	v_mov_b32_e32 v173, v175
	v_pk_add_f32 v[112:113], v[112:113], v[168:169]
	v_pk_add_f32 v[114:115], v[114:115], v[172:173]
	v_pk_mul_f32 v[96:97], v[96:97], v[116:117] op_sel_hi:[1,0]
	v_pk_mul_f32 v[98:99], v[98:99], v[116:117] op_sel_hi:[1,0]
	v_mov_b32_e32 v116, v114
	v_mov_b32_e32 v117, v112
	v_mov_b32_e32 v112, v115
	v_pk_add_f32 v[112:113], v[116:117], v[112:113]
	v_pk_mul_f32 v[102:103], v[102:103], v[110:111]
	v_pk_mul_f32 v[100:101], v[100:101], v[108:109]
	v_pk_mul_f32 v[108:109], v[106:107], s[38:39] op_sel_hi:[1,0]
	v_pk_mul_f32 v[110:111], v[104:105], s[38:39] op_sel_hi:[1,0]
	ds_bpermute_b32 v115, v165, v113
	ds_bpermute_b32 v114, v165, v112
	v_exp_f32_e32 v110, v110
	v_exp_f32_e32 v108, v108
	v_exp_f32_e32 v109, v109
	v_exp_f32_e32 v111, v111
	s_waitcnt lgkmcnt(0)
	v_pk_add_f32 v[112:113], v[112:113], v[114:115]
	ds_bpermute_b32 v115, v164, v113
	v_pk_add_f32 v[108:109], v[108:109], 1.0 op_sel_hi:[1,0]
	v_pk_add_f32 v[110:111], v[110:111], 1.0 op_sel_hi:[1,0]
	v_rcp_f32_e32 v108, v108
	v_rcp_f32_e32 v110, v110
	v_rcp_f32_e32 v111, v111
	v_rcp_f32_e32 v109, v109
	ds_bpermute_b32 v114, v164, v112
	v_pk_mul_f32 v[104:105], v[104:105], v[110:111]
	v_pk_mul_f32 v[106:107], v[106:107], v[108:109]
	s_nop 0
	v_pk_mul_f32 v[106:107], v[98:99], v[106:107]
	v_pk_mul_f32 v[98:99], v[96:97], v[104:105]
	s_waitcnt lgkmcnt(0)
	v_pk_add_f32 v[96:97], v[112:113], v[114:115]
	v_cvt_pk_bf16_f32 v98, v98, v99
	v_pk_fma_f32 v[104:105], v[96:97], s[74:75], v[156:157] op_sel_hi:[1,0,0]
	v_cvt_pk_bf16_f32 v97, v102, v103
	v_mul_f32_e32 v96, 0x4b800000, v105
	v_cmp_gt_f32_e32 vcc, s25, v105
	s_nop 1
	v_cndmask_b32_e32 v96, v105, v96, vcc
	v_rsq_f32_e32 v105, v96
	v_cvt_pk_bf16_f32 v96, v100, v101
	v_mul_f32_e32 v99, 0x45800000, v105
	v_cndmask_b32_e32 v100, v105, v99, vcc
	v_pk_mul_f32 v[92:93], v[92:93], v[100:101] op_sel_hi:[1,0]
	v_pk_mul_f32 v[94:95], v[94:95], v[100:101] op_sel_hi:[1,0]
	v_pk_mul_f32 v[108:109], v[92:93], s[38:39] op_sel_hi:[1,0]
	v_pk_mul_f32 v[102:103], v[94:95], s[38:39] op_sel_hi:[1,0]
	v_exp_f32_e32 v108, v108
	v_exp_f32_e32 v102, v102
	v_exp_f32_e32 v103, v103
	v_exp_f32_e32 v109, v109
	v_cvt_pk_bf16_f32 v99, v106, v107
	global_store_dwordx4 v[160:161], v[96:99], off offset:2048 nt
	v_pk_mul_f32 v[88:89], v[88:89], v[100:101] op_sel_hi:[1,0]
	v_pk_mul_f32 v[90:91], v[90:91], v[100:101] op_sel_hi:[1,0]
	v_pk_add_f32 v[96:97], v[102:103], 1.0 op_sel_hi:[1,0]
	v_pk_add_f32 v[98:99], v[108:109], 1.0 op_sel_hi:[1,0]
	v_rcp_f32_e32 v96, v96
	v_rcp_f32_e32 v98, v98
	v_rcp_f32_e32 v99, v99
	v_rcp_f32_e32 v97, v97
	v_pk_mul_f32 v[84:85], v[84:85], v[100:101] op_sel_hi:[1,0]
	v_pk_mul_f32 v[86:87], v[86:87], v[100:101] op_sel_hi:[1,0]
	v_pk_mul_f32 v[92:93], v[92:93], v[98:99]
	v_pk_mul_f32 v[94:95], v[94:95], v[96:97]
	v_pk_mul_f32 v[96:97], v[90:91], s[38:39] op_sel_hi:[1,0]
	v_pk_mul_f32 v[98:99], v[88:89], s[38:39] op_sel_hi:[1,0]
	v_exp_f32_e32 v96, v96
	v_exp_f32_e32 v98, v98
	v_exp_f32_e32 v97, v97
	v_exp_f32_e32 v99, v99
	v_pk_mul_f32 v[86:87], v[86:87], v[94:95]
	v_pk_mul_f32 v[84:85], v[84:85], v[92:93]
	v_pk_add_f32 v[92:93], v[96:97], 1.0 op_sel_hi:[1,0]
	v_pk_add_f32 v[94:95], v[98:99], 1.0 op_sel_hi:[1,0]
	v_rcp_f32_e32 v92, v92
	v_rcp_f32_e32 v94, v94
	v_rcp_f32_e32 v95, v95
	v_rcp_f32_e32 v93, v93
	v_pk_mul_f32 v[80:81], v[80:81], v[100:101] op_sel_hi:[1,0]
	v_pk_mul_f32 v[82:83], v[82:83], v[100:101] op_sel_hi:[1,0]
	v_pk_mul_f32 v[88:89], v[88:89], v[94:95]
	v_pk_mul_f32 v[90:91], v[90:91], v[92:93]
	v_cmp_gt_f32_e32 vcc, s25, v104
	v_pk_mul_f32 v[90:91], v[82:83], v[90:91]
	v_pk_mul_f32 v[82:83], v[80:81], v[88:89]
	v_mul_f32_e32 v81, 0x4b800000, v104
	v_cndmask_b32_e32 v81, v104, v81, vcc
	v_cvt_pk_bf16_f32 v80, v84, v85
	v_rsq_f32_e32 v84, v81
	v_cvt_pk_bf16_f32 v81, v86, v87
	v_cvt_pk_bf16_f32 v82, v82, v83
	v_cvt_pk_bf16_f32 v83, v90, v91
	v_mul_f32_e32 v85, 0x45800000, v84
	v_cndmask_b32_e32 v84, v84, v85, vcc
	v_pk_mul_f32 v[76:77], v[76:77], v[84:85] op_sel_hi:[1,0]
	v_pk_mul_f32 v[78:79], v[78:79], v[84:85] op_sel_hi:[1,0]
	v_pk_mul_f32 v[88:89], v[76:77], s[38:39] op_sel_hi:[1,0]
	v_pk_mul_f32 v[86:87], v[78:79], s[38:39] op_sel_hi:[1,0]
; __device__ __forceinline__ v4u pack8(const float* x) { v4u o; o.x = pk2(x[0], x[1]); o.y = pk2(x[2], x[3]); o.z = pk2(x[4], x[5]); o.w = pk2(x[6], x[7]); return o; }
; __device__ __forceinline__ size_t tl(int row, int col, int K) { return (size_t)(row >> 8) * ((size_t)256 * K) + (size_t)(col >> 6) * (256 * 64) + (size_t)((row & 255) * 64 + (col & 63)); }
; __device__ __forceinline__ float rstd_from_quarter(const v4f a, int ln) {
;     float s = (a.x + a.y) + (a.z + a.w);
;     s += __int_as_float(__builtin_amdgcn_ds_bpermute((ln ^ 16) << 2, __float_as_int(s))); s += __int_as_float(__builtin_amdgcn_ds_bpermute((ln ^ 32) << 2, __float_as_int(s)));
;     return rsqrtf(s * (1.0f / DM) + EPS);
; }
;     __device__ __forceinline__ void operator()(const f32x4 (&acc)[2][2][4][2], const Unit& u, int wr, int wc, int, int) const {
;     ...
;         for (int ai = 0; ai < 2; ++ai)
; #pragma unroll
;             for (int m = 0; m < 4; ++m) {
;                 const int row = row0 + ai * HALF + m * 16; const float rs = rstd_from_quarter(pq[ai][m], fq * 16 + fr);
;                 float h[8];
; #pragma unroll
;                 for (int n = 0; n < 2; ++n) { const f32x4 g = acc[ai][0][m][n] * rs, uu = acc[ai][1][m][n] * rs; const f32x4 hv = (g * sigmoid4(g)) * uu;
;                     h[n * 4 + 0] = hv[0]; h[n * 4 + 1] = hv[1]; h[n * 4 + 2] = hv[2]; h[n * 4 + 3] = hv[3]; }
;                 __builtin_nontemporal_store(pack8(h), (u32x4*)(O + tl(row, col0, FF)));
	v_exp_f32_e32 v88, v88
	v_exp_f32_e32 v89, v89
	v_exp_f32_e32 v86, v86
	v_exp_f32_e32 v87, v87
	v_add_co_u32_e32 v90, vcc, s85, v160
	v_pk_mul_f32 v[72:73], v[72:73], v[84:85] op_sel_hi:[1,0]
	s_nop 0
	v_addc_co_u32_e32 v91, vcc, 0, v161, vcc
	global_store_dwordx4 v[90:91], v[80:83], off nt
	v_pk_mul_f32 v[74:75], v[74:75], v[84:85] op_sel_hi:[1,0]
	v_pk_mul_f32 v[68:69], v[68:69], v[84:85] op_sel_hi:[1,0]
	v_pk_add_f32 v[80:81], v[86:87], 1.0 op_sel_hi:[1,0]
	v_pk_add_f32 v[82:83], v[88:89], 1.0 op_sel_hi:[1,0]
	v_rcp_f32_e32 v80, v80
	v_rcp_f32_e32 v82, v82
	v_rcp_f32_e32 v83, v83
	v_rcp_f32_e32 v81, v81
	v_pk_mul_f32 v[70:71], v[70:71], v[84:85] op_sel_hi:[1,0]
	v_pk_mul_f32 v[64:65], v[64:65], v[84:85] op_sel_hi:[1,0]
	v_pk_mul_f32 v[76:77], v[76:77], v[82:83]
	v_pk_mul_f32 v[78:79], v[78:79], v[80:81]
	v_pk_mul_f32 v[80:81], v[74:75], s[38:39] op_sel_hi:[1,0]
	v_pk_mul_f32 v[82:83], v[72:73], s[38:39] op_sel_hi:[1,0]
	v_exp_f32_e32 v80, v80
	v_exp_f32_e32 v82, v82
	v_exp_f32_e32 v81, v81
	v_exp_f32_e32 v83, v83
	v_pk_mul_f32 v[70:71], v[70:71], v[78:79]
	v_pk_mul_f32 v[68:69], v[68:69], v[76:77]
	v_pk_add_f32 v[76:77], v[80:81], 1.0 op_sel_hi:[1,0]
	v_pk_add_f32 v[78:79], v[82:83], 1.0 op_sel_hi:[1,0]
	v_rcp_f32_e32 v76, v76
	v_rcp_f32_e32 v78, v78
	v_rcp_f32_e32 v79, v79
	v_rcp_f32_e32 v77, v77
	v_pk_mul_f32 v[66:67], v[66:67], v[84:85] op_sel_hi:[1,0]
	v_pk_mul_f32 v[72:73], v[72:73], v[78:79]
	v_pk_mul_f32 v[74:75], v[74:75], v[76:77]
	s_nop 0
	v_pk_mul_f32 v[74:75], v[66:67], v[74:75]
	v_pk_mul_f32 v[66:67], v[64:65], v[72:73]
	v_mov_b32_e32 v64, v141
	v_mov_b32_e32 v65, v142
	v_mov_b32_e32 v141, v143
	v_mov_b32_e32 v72, v137
	v_mov_b32_e32 v73, v138
	v_mov_b32_e32 v137, v139
	v_pk_add_f32 v[64:65], v[64:65], v[140:141]
	v_pk_add_f32 v[72:73], v[72:73], v[136:137]
	v_mov_b32_e32 v77, v64
	v_mov_b32_e32 v76, v72
	v_mov_b32_e32 v64, v73
	v_pk_add_f32 v[72:73], v[76:77], v[64:65]
	ds_bpermute_b32 v77, v165, v73
	ds_bpermute_b32 v76, v165, v72
	v_cvt_pk_bf16_f32 v64, v68, v69
	v_cvt_pk_bf16_f32 v65, v70, v71
	v_cvt_pk_bf16_f32 v66, v66, v67
	v_cvt_pk_bf16_f32 v67, v74, v75
	s_waitcnt lgkmcnt(0)
	v_pk_add_f32 v[68:69], v[72:73], v[76:77]
	ds_bpermute_b32 v71, v164, v69
	ds_bpermute_b32 v70, v164, v68
	global_store_dwordx4 v[90:91], v[64:67], off offset:2048 nt
	s_nop 1
	v_lshlrev_b32_e32 v64, 6, v158
	v_and_or_b32 v72, v64, s84, v166
	s_waitcnt lgkmcnt(0)
	v_pk_add_f32 v[64:65], v[68:69], v[70:71]
	v_lshlrev_b32_e32 v220, 1, v72
	v_pk_fma_f32 v[64:65], v[64:65], s[74:75], v[156:157] op_sel_hi:[1,0,0]
	v_lshrrev_b32_e32 v66, 8, v158
	s_nop 1
	v_rsq_f32_e32 v65, v65
	v_mul_hi_i32_i24_e32 v67, 0x160000, v66
	v_mul_i32_i24_e32 v66, 0x160000, v66
	s_nop 0
	v_mov_b32_e32 v68, v65
	v_pk_mul_f32 v[70:71], v[60:61], v[68:69] op_sel_hi:[1,0]
	v_pk_mul_f32 v[62:63], v[62:63], v[68:69] op_sel_hi:[1,0]
	v_pk_mul_f32 v[72:73], v[70:71], s[38:39] op_sel_hi:[1,0]
	v_pk_mul_f32 v[60:61], v[62:63], s[38:39] op_sel_hi:[1,0]
	v_exp_f32_e32 v72, v72
	v_exp_f32_e32 v74, v60
	v_exp_f32_e32 v75, v61
	v_exp_f32_e32 v73, v73
	v_lshl_add_u64 v[60:61], s[16:17], 0, v[220:221]
	v_lshl_add_u64 v[60:61], v[60:61], 0, v[66:67]
	v_pk_add_f32 v[66:67], v[74:75], 1.0 op_sel_hi:[1,0]
	v_pk_add_f32 v[72:73], v[72:73], 1.0 op_sel_hi:[1,0]
	v_rcp_f32_e32 v66, v66
	v_rcp_f32_e32 v72, v72
	v_rcp_f32_e32 v73, v73
	v_rcp_f32_e32 v67, v67
	v_pk_mul_f32 v[56:57], v[56:57], v[68:69] op_sel_hi:[1,0]
	v_pk_mul_f32 v[58:59], v[58:59], v[68:69] op_sel_hi:[1,0]
	v_pk_mul_f32 v[70:71], v[70:71], v[72:73]
	v_pk_mul_f32 v[62:63], v[62:63], v[66:67]
	v_pk_mul_f32 v[66:67], v[58:59], s[38:39] op_sel_hi:[1,0]
	v_pk_mul_f32 v[72:73], v[56:57], s[38:39] op_sel_hi:[1,0]
	v_exp_f32_e32 v66, v66
	v_exp_f32_e32 v72, v72
	v_exp_f32_e32 v67, v67
	v_exp_f32_e32 v73, v73
	v_pk_mul_f32 v[54:55], v[54:55], v[68:69] op_sel_hi:[1,0]
	v_pk_mul_f32 v[48:49], v[48:49], v[68:69] op_sel_hi:[1,0]
	v_pk_mul_f32 v[54:55], v[54:55], v[62:63]
	v_pk_add_f32 v[62:63], v[66:67], 1.0 op_sel_hi:[1,0]
	v_pk_add_f32 v[66:67], v[72:73], 1.0 op_sel_hi:[1,0]
	v_rcp_f32_e32 v62, v62
	v_rcp_f32_e32 v66, v66
	v_rcp_f32_e32 v67, v67
	v_rcp_f32_e32 v63, v63
	v_pk_mul_f32 v[50:51], v[50:51], v[68:69] op_sel_hi:[1,0]
	v_cmp_gt_f32_e32 vcc, s25, v64
	v_pk_mul_f32 v[56:57], v[56:57], v[66:67]
	v_pk_mul_f32 v[58:59], v[58:59], v[62:63]
	v_pk_mul_f32 v[52:53], v[52:53], v[68:69] op_sel_hi:[1,0]
	v_pk_mul_f32 v[58:59], v[50:51], v[58:59]
	v_pk_mul_f32 v[50:51], v[48:49], v[56:57]
	v_mul_f32_e32 v48, 0x4b800000, v64
	v_cndmask_b32_e32 v48, v64, v48, vcc
	v_rsq_f32_e32 v56, v48
	v_pk_mul_f32 v[52:53], v[52:53], v[70:71]
	v_cvt_pk_bf16_f32 v50, v50, v51
	v_cvt_pk_bf16_f32 v48, v52, v53
	v_mul_f32_e32 v51, 0x45800000, v56
	v_cndmask_b32_e32 v52, v56, v51, vcc
	v_pk_mul_f32 v[44:45], v[44:45], v[52:53] op_sel_hi:[1,0]
	v_pk_mul_f32 v[46:47], v[46:47], v[52:53] op_sel_hi:[1,0]
	v_cvt_pk_bf16_f32 v49, v54, v55
	v_pk_mul_f32 v[54:55], v[46:47], s[38:39] op_sel_hi:[1,0]
	v_pk_mul_f32 v[56:57], v[44:45], s[38:39] op_sel_hi:[1,0]
	v_exp_f32_e32 v54, v54
	v_exp_f32_e32 v56, v56
	v_exp_f32_e32 v55, v55
	v_exp_f32_e32 v57, v57
	v_cvt_pk_bf16_f32 v51, v58, v59
	global_store_dwordx4 v[60:61], v[48:51], off nt
	v_pk_mul_f32 v[36:37], v[36:37], v[52:53] op_sel_hi:[1,0]
	v_pk_mul_f32 v[38:39], v[38:39], v[52:53] op_sel_hi:[1,0]
	v_pk_add_f32 v[48:49], v[54:55], 1.0 op_sel_hi:[1,0]
	v_pk_add_f32 v[50:51], v[56:57], 1.0 op_sel_hi:[1,0]
	v_rcp_f32_e32 v48, v48
	v_rcp_f32_e32 v50, v50
	v_rcp_f32_e32 v51, v51
	v_rcp_f32_e32 v49, v49
	v_pk_mul_f32 v[40:41], v[40:41], v[52:53] op_sel_hi:[1,0]
	v_pk_mul_f32 v[42:43], v[42:43], v[52:53] op_sel_hi:[1,0]
	v_pk_mul_f32 v[44:45], v[44:45], v[50:51]
	v_pk_mul_f32 v[46:47], v[46:47], v[48:49]
	v_mov_b32_e32 v48, v133
	v_mov_b32_e32 v49, v134
	v_mov_b32_e32 v133, v135
	v_mov_b32_e32 v50, v129
	v_mov_b32_e32 v51, v130
	v_mov_b32_e32 v129, v131
	v_pk_add_f32 v[48:49], v[48:49], v[132:133]
	v_pk_add_f32 v[50:51], v[50:51], v[128:129]
	v_pk_mul_f32 v[32:33], v[32:33], v[52:53] op_sel_hi:[1,0]
	v_pk_mul_f32 v[34:35], v[34:35], v[52:53] op_sel_hi:[1,0]
	v_mov_b32_e32 v52, v50
	v_mov_b32_e32 v53, v48
	v_mov_b32_e32 v48, v51
	v_pk_add_f32 v[48:49], v[52:53], v[48:49]
	v_pk_mul_f32 v[38:39], v[38:39], v[46:47]
	v_pk_mul_f32 v[36:37], v[36:37], v[44:45]
	v_pk_mul_f32 v[44:45], v[42:43], s[38:39] op_sel_hi:[1,0]
	v_pk_mul_f32 v[46:47], v[40:41], s[38:39] op_sel_hi:[1,0]
	ds_bpermute_b32 v51, v165, v49
	ds_bpermute_b32 v50, v165, v48
	v_exp_f32_e32 v46, v46
	v_exp_f32_e32 v44, v44
	v_exp_f32_e32 v45, v45
	v_exp_f32_e32 v47, v47
	s_waitcnt lgkmcnt(0)
; __device__ __forceinline__ v4u pack8(const float* x) { v4u o; o.x = pk2(x[0], x[1]); o.y = pk2(x[2], x[3]); o.z = pk2(x[4], x[5]); o.w = pk2(x[6], x[7]); return o; }
; __device__ __forceinline__ size_t tl(int row, int col, int K) { return (size_t)(row >> 8) * ((size_t)256 * K) + (size_t)(col >> 6) * (256 * 64) + (size_t)((row & 255) * 64 + (col & 63)); }
; __device__ __forceinline__ float rstd_from_quarter(const v4f a, int ln) {
;     float s = (a.x + a.y) + (a.z + a.w);
;     s += __int_as_float(__builtin_amdgcn_ds_bpermute((ln ^ 16) << 2, __float_as_int(s))); s += __int_as_float(__builtin_amdgcn_ds_bpermute((ln ^ 32) << 2, __float_as_int(s)));
;     return rsqrtf(s * (1.0f / DM) + EPS);
; }
;     __device__ __forceinline__ void operator()(const f32x4 (&acc)[2][2][4][2], const Unit& u, int wr, int wc, int, int) const {
;     ...
;         for (int ai = 0; ai < 2; ++ai)
; #pragma unroll
;             for (int m = 0; m < 4; ++m) {
;                 const int row = row0 + ai * HALF + m * 16; const float rs = rstd_from_quarter(pq[ai][m], fq * 16 + fr);
;                 float h[8];
; #pragma unroll
;                 for (int n = 0; n < 2; ++n) { const f32x4 g = acc[ai][0][m][n] * rs, uu = acc[ai][1][m][n] * rs; const f32x4 hv = (g * sigmoid4(g)) * uu;
;                     h[n * 4 + 0] = hv[0]; h[n * 4 + 1] = hv[1]; h[n * 4 + 2] = hv[2]; h[n * 4 + 3] = hv[3]; }
;                 __builtin_nontemporal_store(pack8(h), (u32x4*)(O + tl(row, col0, FF)));
	v_pk_add_f32 v[48:49], v[48:49], v[50:51]
	ds_bpermute_b32 v51, v164, v49
	v_pk_add_f32 v[44:45], v[44:45], 1.0 op_sel_hi:[1,0]
	v_pk_add_f32 v[46:47], v[46:47], 1.0 op_sel_hi:[1,0]
	v_rcp_f32_e32 v44, v44
	v_rcp_f32_e32 v46, v46
	v_rcp_f32_e32 v47, v47
	v_rcp_f32_e32 v45, v45
	ds_bpermute_b32 v50, v164, v48
	v_pk_mul_f32 v[40:41], v[40:41], v[46:47]
	v_pk_mul_f32 v[42:43], v[42:43], v[44:45]
	s_nop 0
	v_pk_mul_f32 v[42:43], v[34:35], v[42:43]
	v_pk_mul_f32 v[34:35], v[32:33], v[40:41]
	s_waitcnt lgkmcnt(0)
	v_pk_add_f32 v[32:33], v[48:49], v[50:51]
	v_cvt_pk_bf16_f32 v34, v34, v35
	v_pk_fma_f32 v[40:41], v[32:33], s[74:75], v[156:157] op_sel_hi:[1,0,0]
	v_cvt_pk_bf16_f32 v33, v38, v39
	v_mul_f32_e32 v32, 0x4b800000, v41
	v_cmp_gt_f32_e32 vcc, s25, v41
	s_nop 1
	v_cndmask_b32_e32 v32, v41, v32, vcc
	v_rsq_f32_e32 v41, v32
	v_cvt_pk_bf16_f32 v32, v36, v37
	v_mul_f32_e32 v35, 0x45800000, v41
	v_cndmask_b32_e32 v36, v41, v35, vcc
	v_pk_mul_f32 v[28:29], v[28:29], v[36:37] op_sel_hi:[1,0]
	v_pk_mul_f32 v[30:31], v[30:31], v[36:37] op_sel_hi:[1,0]
	v_pk_mul_f32 v[44:45], v[28:29], s[38:39] op_sel_hi:[1,0]
	v_pk_mul_f32 v[38:39], v[30:31], s[38:39] op_sel_hi:[1,0]
	v_exp_f32_e32 v44, v44
	v_exp_f32_e32 v38, v38
	v_exp_f32_e32 v39, v39
	v_exp_f32_e32 v45, v45
	v_cvt_pk_bf16_f32 v35, v42, v43
	global_store_dwordx4 v[60:61], v[32:35], off offset:2048 nt
	v_pk_mul_f32 v[24:25], v[24:25], v[36:37] op_sel_hi:[1,0]
	v_pk_mul_f32 v[26:27], v[26:27], v[36:37] op_sel_hi:[1,0]
	v_pk_add_f32 v[32:33], v[38:39], 1.0 op_sel_hi:[1,0]
	v_pk_add_f32 v[34:35], v[44:45], 1.0 op_sel_hi:[1,0]
	v_rcp_f32_e32 v32, v32
	v_rcp_f32_e32 v34, v34
	v_rcp_f32_e32 v35, v35
	v_rcp_f32_e32 v33, v33
	v_pk_mul_f32 v[20:21], v[20:21], v[36:37] op_sel_hi:[1,0]
	v_pk_mul_f32 v[22:23], v[22:23], v[36:37] op_sel_hi:[1,0]
	v_pk_mul_f32 v[28:29], v[28:29], v[34:35]
	v_pk_mul_f32 v[30:31], v[30:31], v[32:33]
	v_pk_mul_f32 v[32:33], v[26:27], s[38:39] op_sel_hi:[1,0]
	v_pk_mul_f32 v[34:35], v[24:25], s[38:39] op_sel_hi:[1,0]
	v_exp_f32_e32 v32, v32
	v_exp_f32_e32 v34, v34
	v_exp_f32_e32 v33, v33
	v_exp_f32_e32 v35, v35
	v_pk_mul_f32 v[22:23], v[22:23], v[30:31]
	v_pk_mul_f32 v[20:21], v[20:21], v[28:29]
	v_pk_add_f32 v[28:29], v[32:33], 1.0 op_sel_hi:[1,0]
	v_pk_add_f32 v[30:31], v[34:35], 1.0 op_sel_hi:[1,0]
	v_rcp_f32_e32 v28, v28
	v_rcp_f32_e32 v30, v30
	v_rcp_f32_e32 v31, v31
	v_rcp_f32_e32 v29, v29
	v_pk_mul_f32 v[16:17], v[16:17], v[36:37] op_sel_hi:[1,0]
	v_pk_mul_f32 v[18:19], v[18:19], v[36:37] op_sel_hi:[1,0]
	v_pk_mul_f32 v[24:25], v[24:25], v[30:31]
	v_pk_mul_f32 v[26:27], v[26:27], v[28:29]
	v_cmp_gt_f32_e32 vcc, s25, v40
	v_pk_mul_f32 v[26:27], v[18:19], v[26:27]
	v_pk_mul_f32 v[18:19], v[16:17], v[24:25]
	v_mul_f32_e32 v17, 0x4b800000, v40
	v_cndmask_b32_e32 v17, v40, v17, vcc
	v_cvt_pk_bf16_f32 v16, v20, v21
	v_rsq_f32_e32 v20, v17
	v_cvt_pk_bf16_f32 v17, v22, v23
	v_cvt_pk_bf16_f32 v18, v18, v19
	v_cvt_pk_bf16_f32 v19, v26, v27
	v_mul_f32_e32 v21, 0x45800000, v20
	v_cndmask_b32_e32 v20, v20, v21, vcc
	v_pk_mul_f32 v[12:13], v[12:13], v[20:21] op_sel_hi:[1,0]
	v_pk_mul_f32 v[14:15], v[14:15], v[20:21] op_sel_hi:[1,0]
	v_pk_mul_f32 v[24:25], v[12:13], s[38:39] op_sel_hi:[1,0]
	v_pk_mul_f32 v[22:23], v[14:15], s[38:39] op_sel_hi:[1,0]
	v_exp_f32_e32 v24, v24
	v_exp_f32_e32 v25, v25
	v_exp_f32_e32 v22, v22
	v_exp_f32_e32 v23, v23
	v_add_co_u32_e32 v26, vcc, s85, v60
	v_pk_mul_f32 v[8:9], v[8:9], v[20:21] op_sel_hi:[1,0]
	s_nop 0
	v_addc_co_u32_e32 v27, vcc, 0, v61, vcc
	global_store_dwordx4 v[26:27], v[16:19], off nt
	v_pk_mul_f32 v[10:11], v[10:11], v[20:21] op_sel_hi:[1,0]
	v_pk_mul_f32 v[4:5], v[4:5], v[20:21] op_sel_hi:[1,0]
	v_pk_add_f32 v[16:17], v[22:23], 1.0 op_sel_hi:[1,0]
	v_pk_add_f32 v[18:19], v[24:25], 1.0 op_sel_hi:[1,0]
	v_rcp_f32_e32 v16, v16
	v_rcp_f32_e32 v18, v18
	v_rcp_f32_e32 v19, v19
	v_rcp_f32_e32 v17, v17
	v_pk_mul_f32 v[6:7], v[6:7], v[20:21] op_sel_hi:[1,0]
	v_pk_mul_f32 v[0:1], v[0:1], v[20:21] op_sel_hi:[1,0]
	v_pk_mul_f32 v[12:13], v[12:13], v[18:19]
	v_pk_mul_f32 v[14:15], v[14:15], v[16:17]
	v_pk_mul_f32 v[16:17], v[10:11], s[38:39] op_sel_hi:[1,0]
	v_pk_mul_f32 v[18:19], v[8:9], s[38:39] op_sel_hi:[1,0]
	v_exp_f32_e32 v16, v16
	v_exp_f32_e32 v18, v18
	v_exp_f32_e32 v17, v17
	v_exp_f32_e32 v19, v19
	v_pk_mul_f32 v[6:7], v[6:7], v[14:15]
	v_pk_mul_f32 v[4:5], v[4:5], v[12:13]
	v_pk_add_f32 v[12:13], v[16:17], 1.0 op_sel_hi:[1,0]
	v_pk_add_f32 v[14:15], v[18:19], 1.0 op_sel_hi:[1,0]
	v_rcp_f32_e32 v12, v12
	v_rcp_f32_e32 v14, v14
	v_rcp_f32_e32 v15, v15
	v_rcp_f32_e32 v13, v13
	v_pk_mul_f32 v[2:3], v[2:3], v[20:21] op_sel_hi:[1,0]
	s_andn2_b64 vcc, exec, s[2:3]
	v_pk_mul_f32 v[8:9], v[8:9], v[14:15]
	v_pk_mul_f32 v[10:11], v[10:11], v[12:13]
	s_mov_b64 s[2:3], -1
	v_pk_mul_f32 v[10:11], v[2:3], v[10:11]
	v_pk_mul_f32 v[2:3], v[0:1], v[8:9]
	v_cvt_pk_bf16_f32 v0, v4, v5
	v_cvt_pk_bf16_f32 v1, v6, v7
	v_cvt_pk_bf16_f32 v2, v2, v3
	v_cvt_pk_bf16_f32 v3, v10, v11
	global_store_dwordx4 v[26:27], v[0:3], off offset:2048 nt
	s_cbranch_vccnz .LBB0_1352
	s_andn2_b64 vcc, exec, s[0:1]
	s_cbranch_vccnz .LBB0_1351
	s_barrier
	s_branch .LBB0_1351
